# NSA phase bias-table fill: 32 loads issued up front instead of 16 serialised round trips (on top of opt9)
# speedup vs baseline: 1.0031x; 1.0031x over previous
; __device__ __forceinline__ void phase_nsa_mfma(const PT a, unsigned char* ldsb, int tid, int lane, int wave, int bid, int nblk) {
;     ...
;         if (g != gcur) { __syncthreads();
;             for (int i = tid; i < 8 * 2048; i += 512) tabs[i] = biasT[(24 + g * 8 + (i >> 11)) * BT + (i & 2047)] * LOG2E; for (int i = tid; i < 2048; i += 512) bk[i] = (unsigned char)t5_bucket(i); gcur = g; }
.LBB0_115:
	s_mul_i32 s9, s8, s12
	s_lshl_b32 s9, s9, 2
	v_lshl_add_u32 v6, v112, 2, s9
	v_add_u32_e32 v9, 0x1000, v6
	global_load_dword v16, v6, s[14:15]
	global_load_dword v17, v6, s[14:15] offset:2048
	global_load_dword v18, v9, s[14:15]
	global_load_dword v19, v9, s[14:15] offset:2048
	v_add_u32_e32 v10, 0x2100, v6
	v_add_u32_e32 v11, 0x3100, v6
	global_load_dword v20, v10, s[14:15]
	global_load_dword v21, v10, s[14:15] offset:2048
	global_load_dword v22, v11, s[14:15]
	global_load_dword v23, v11, s[14:15] offset:2048
	v_add_u32_e32 v8, 0x4200, v6
	v_add_u32_e32 v9, 0x5200, v6
	global_load_dword v24, v8, s[14:15]
	global_load_dword v25, v8, s[14:15] offset:2048
	global_load_dword v26, v9, s[14:15]
	global_load_dword v27, v9, s[14:15] offset:2048
	v_add_u32_e32 v10, 0x6300, v6
	v_add_u32_e32 v11, 0x7300, v6
	global_load_dword v28, v10, s[14:15]
	global_load_dword v29, v10, s[14:15] offset:2048
	global_load_dword v30, v11, s[14:15]
	global_load_dword v31, v11, s[14:15] offset:2048
	v_add_u32_e32 v8, 0x8400, v6
	v_add_u32_e32 v9, 0x9400, v6
	global_load_dword v32, v8, s[14:15]
	global_load_dword v33, v8, s[14:15] offset:2048
	global_load_dword v34, v9, s[14:15]
	global_load_dword v35, v9, s[14:15] offset:2048
	v_add_u32_e32 v10, 0xa500, v6
	v_add_u32_e32 v11, 0xb500, v6
	global_load_dword v36, v10, s[14:15]
	global_load_dword v37, v10, s[14:15] offset:2048
	global_load_dword v38, v11, s[14:15]
	global_load_dword v39, v11, s[14:15] offset:2048
	v_add_u32_e32 v8, 0xc600, v6
	v_add_u32_e32 v9, 0xd600, v6
	global_load_dword v40, v8, s[14:15]
	global_load_dword v41, v8, s[14:15] offset:2048
	global_load_dword v42, v9, s[14:15]
	global_load_dword v43, v9, s[14:15] offset:2048
	v_add_u32_e32 v10, 0xe700, v6
	v_add_u32_e32 v11, 0xf700, v6
	global_load_dword v44, v10, s[14:15]
	global_load_dword v45, v10, s[14:15] offset:2048
	global_load_dword v46, v11, s[14:15]
	global_load_dword v47, v11, s[14:15] offset:2048
	s_waitcnt vmcnt(0)
	v_pk_mul_f32 v[16:17], v[16:17], s[28:29] op_sel_hi:[1,0]
	v_pk_mul_f32 v[18:19], v[18:19], s[28:29] op_sel_hi:[1,0]
	v_pk_mul_f32 v[20:21], v[20:21], s[28:29] op_sel_hi:[1,0]
	v_pk_mul_f32 v[22:23], v[22:23], s[28:29] op_sel_hi:[1,0]
	v_pk_mul_f32 v[24:25], v[24:25], s[28:29] op_sel_hi:[1,0]
	v_pk_mul_f32 v[26:27], v[26:27], s[28:29] op_sel_hi:[1,0]
	v_pk_mul_f32 v[28:29], v[28:29], s[28:29] op_sel_hi:[1,0]
	v_pk_mul_f32 v[30:31], v[30:31], s[28:29] op_sel_hi:[1,0]
	v_pk_mul_f32 v[32:33], v[32:33], s[28:29] op_sel_hi:[1,0]
	v_pk_mul_f32 v[34:35], v[34:35], s[28:29] op_sel_hi:[1,0]
	v_pk_mul_f32 v[36:37], v[36:37], s[28:29] op_sel_hi:[1,0]
	v_pk_mul_f32 v[38:39], v[38:39], s[28:29] op_sel_hi:[1,0]
	v_pk_mul_f32 v[40:41], v[40:41], s[28:29] op_sel_hi:[1,0]
	v_pk_mul_f32 v[42:43], v[42:43], s[28:29] op_sel_hi:[1,0]
	v_pk_mul_f32 v[44:45], v[44:45], s[28:29] op_sel_hi:[1,0]
	v_pk_mul_f32 v[46:47], v[46:47], s[28:29] op_sel_hi:[1,0]
	ds_write2st64_b32 v5, v16, v17 offset0:0 offset1:8
	ds_write2st64_b32 v5, v18, v19 offset0:16 offset1:24
	ds_write2st64_b32 v5, v20, v21 offset0:32 offset1:40
	ds_write2st64_b32 v5, v22, v23 offset0:48 offset1:56
	ds_write2st64_b32 v5, v24, v25 offset0:64 offset1:72
	ds_write2st64_b32 v5, v26, v27 offset0:80 offset1:88
	ds_write2st64_b32 v5, v28, v29 offset0:96 offset1:104
	ds_write2st64_b32 v5, v30, v31 offset0:112 offset1:120
	ds_write2st64_b32 v5, v32, v33 offset0:128 offset1:136
	ds_write2st64_b32 v5, v34, v35 offset0:144 offset1:152
	ds_write2st64_b32 v5, v36, v37 offset0:160 offset1:168
	ds_write2st64_b32 v5, v38, v39 offset0:176 offset1:184
	ds_write2st64_b32 v5, v40, v41 offset0:192 offset1:200
	ds_write2st64_b32 v5, v42, v43 offset0:208 offset1:216
	ds_write2st64_b32 v5, v44, v45 offset0:224 offset1:232
	ds_write2st64_b32 v5, v46, v47 offset0:240 offset1:248
	s_or_b64 exec, exec, s[6:7]
	v_cmp_ne_u32_e32 vcc, v0, v4
	v_lshl_add_u32 v2, v4, 9, v112
	s_orn2_b64 s[6:7], vcc, exec
